# gdn_chunk_prep: conv taps of channel groups 2 and 3 prefetched with renamed registers (two exposed round trips per job removed)
# speedup vs baseline: 1.0077x; 1.0075x over previous
.LBB0_365:
	s_or_b64 exec, exec, s[86:87]
	s_waitcnt vmcnt(59)
	v_lshlrev_b32_e32 v0, 16, v8
	v_cndmask_b32_e64 v1, 0, v0, s[44:45]
	s_waitcnt vmcnt(57)
	v_lshlrev_b32_e32 v0, 16, v9
	v_cndmask_b32_e64 v8, 0, v0, s[46:47]
	s_waitcnt vmcnt(55)
	v_lshlrev_b32_e32 v0, 16, v49
	v_cndmask_b32_e64 v9, 0, v0, s[48:49]
	s_waitcnt vmcnt(53)
	v_lshlrev_b32_e32 v0, 16, v50
	v_cndmask_b32_e64 v49, 0, v0, s[50:51]
	s_waitcnt vmcnt(50)
	v_lshlrev_b32_e32 v0, 16, v51
	v_cndmask_b32_e64 v50, 0, v0, s[52:53]
	s_waitcnt vmcnt(47)
	v_lshlrev_b32_e32 v0, 16, v52
	s_waitcnt vmcnt(3)
	v_mul_f32_e32 v2, v65, v70
	v_cndmask_b32_e64 v51, 0, v0, s[54:55]
	v_lshlrev_b32_e32 v0, 16, v53
	s_waitcnt vmcnt(2)
	v_fmac_f32_e32 v2, v1, v66
	v_cndmask_b32_e64 v52, 0, v0, s[56:57]
	v_lshlrev_b32_e32 v0, 16, v54
	s_waitcnt vmcnt(1)
	v_fmac_f32_e32 v2, v8, v67
	v_cndmask_b32_e64 v53, 0, v0, s[58:59]
	v_lshlrev_b32_e32 v0, 16, v55
	s_waitcnt vmcnt(0)
	s_mov_b64 s[2:3], 0x1000
	v_lshl_add_u64 v[212:213], v[6:7], 0, s[2:3]
	s_mov_b64 s[2:3], 0x2000
	v_lshl_add_u64 v[214:215], v[6:7], 0, s[2:3]
	global_load_dword v204, v[6:7], off offset:1024
	global_load_dword v205, v[212:213], off
	global_load_dword v206, v[212:213], off offset:3072
	global_load_dword v207, v[214:215], off offset:2048
	global_load_dword v208, v[6:7], off offset:2048
	global_load_dword v209, v[212:213], off offset:1024
	global_load_dword v210, v[214:215], off
	global_load_dword v211, v[214:215], off offset:3072
	v_fmac_f32_e32 v2, v9, v69
	v_cndmask_b32_e64 v54, 0, v0, s[60:61]
	v_lshlrev_b32_e32 v0, 16, v56
	v_mul_f32_e32 v3, 0xbfb8aa3b, v2
	v_cndmask_b32_e64 v55, 0, v0, s[62:63]
	v_lshlrev_b32_e32 v0, 16, v57
	v_exp_f32_e32 v3, v3
	v_cndmask_b32_e64 v56, 0, v0, s[64:65]
	v_lshlrev_b32_e32 v0, 16, v58
	v_cndmask_b32_e64 v57, 0, v0, s[66:67]
	v_lshlrev_b32_e32 v0, 16, v59
	v_cndmask_b32_e64 v58, 0, v0, s[68:69]
	v_lshlrev_b32_e32 v0, 16, v60
	v_cndmask_b32_e64 v59, 0, v0, s[70:71]
	v_lshlrev_b32_e32 v0, 16, v61
	v_add_f32_e32 v3, 1.0, v3
	v_cndmask_b32_e64 v60, 0, v0, s[72:73]
	v_lshlrev_b32_e32 v0, 16, v62
	v_rcp_f32_e32 v3, v3
	v_cndmask_b32_e64 v61, 0, v0, s[74:75]
	v_lshlrev_b32_e32 v0, 16, v63
	s_and_b32 s2, s90, 0xfffffc00
	s_lshl_b32 s3, s26, 8
	v_cndmask_b32_e64 v62, 0, v0, s[76:77]
	v_lshlrev_b32_e32 v0, 16, v64
	s_or_b32 s2, s3, s2
	v_cndmask_b32_e64 v63, 0, v0, s[78:79]
	v_lshlrev_b32_e32 v0, 2, v34
	s_or_b32 s86, s2, s27
	v_mul_f32_e32 v64, v2, v3
	v_mad_u64_u32 v[2:3], s[2:3], v5, s33, v[0:1]
	v_mul_f32_e32 v3, v8, v66
	v_fmac_f32_e32 v3, v1, v65
	v_fmac_f32_e32 v3, v9, v67
	v_fmac_f32_e32 v3, v49, v69
	v_mul_f32_e32 v1, 0xbfb8aa3b, v3
	v_exp_f32_e32 v1, v1
	v_lshlrev_b32_e32 v30, 16, v30
	v_lshlrev_b32_e32 v29, 16, v29
	v_cndmask_b32_e64 v30, 0, v30, s[44:45]
	v_add_f32_e32 v1, 1.0, v1
	v_rcp_f32_e32 v1, v1
	v_cndmask_b32_e64 v29, 0, v29, s[42:43]
	v_lshlrev_b32_e32 v31, 16, v31
	v_cndmask_b32_e64 v31, 0, v31, s[46:47]
	v_mul_f32_e32 v1, v3, v1
	ds_write2_b32 v2, v64, v1 offset1:65
	v_mul_f32_e32 v1, v9, v66
	v_fmac_f32_e32 v1, v8, v65
	v_fmac_f32_e32 v1, v49, v67
	v_fmac_f32_e32 v1, v50, v69
	v_mul_f32_e32 v3, 0xbfb8aa3b, v1
	v_exp_f32_e32 v3, v3
	v_lshlrev_b32_e32 v32, 16, v32
	v_cndmask_b32_e64 v32, 0, v32, s[48:49]
	v_lshlrev_b32_e32 v33, 16, v33
	v_add_f32_e32 v3, 1.0, v3
	v_rcp_f32_e32 v3, v3
	v_cndmask_b32_e64 v33, 0, v33, s[50:51]
	v_lshlrev_b32_e32 v35, 16, v35
	v_cndmask_b32_e64 v35, 0, v35, s[52:53]
	v_mul_f32_e32 v1, v1, v3
	v_mul_f32_e32 v3, v49, v66
	v_fmac_f32_e32 v3, v9, v65
	v_fmac_f32_e32 v3, v50, v67
	v_fmac_f32_e32 v3, v51, v69
	v_mul_f32_e32 v5, 0xbfb8aa3b, v3
	v_exp_f32_e32 v5, v5
	v_lshlrev_b32_e32 v36, 16, v36
	v_cndmask_b32_e64 v36, 0, v36, s[54:55]
	v_lshlrev_b32_e32 v37, 16, v37
	v_add_f32_e32 v5, 1.0, v5
	v_rcp_f32_e32 v5, v5
	v_cndmask_b32_e64 v37, 0, v37, s[56:57]
	v_lshlrev_b32_e32 v38, 16, v38
	v_cndmask_b32_e64 v38, 0, v38, s[58:59]
	v_mul_f32_e32 v3, v3, v5
	ds_write2_b32 v2, v1, v3 offset0:130 offset1:195
	v_mul_f32_e32 v1, v50, v66
	v_fmac_f32_e32 v1, v49, v65
	v_fmac_f32_e32 v1, v51, v67
	v_fmac_f32_e32 v1, v52, v69
	v_mul_f32_e32 v3, 0xbfb8aa3b, v1
	v_exp_f32_e32 v3, v3
	v_lshlrev_b32_e32 v39, 16, v39
	v_cndmask_b32_e64 v39, 0, v39, s[60:61]
	v_lshlrev_b32_e32 v40, 16, v40
	v_add_f32_e32 v3, 1.0, v3
	v_rcp_f32_e32 v3, v3
	v_cndmask_b32_e64 v40, 0, v40, s[62:63]
	v_lshlrev_b32_e32 v41, 16, v41
	v_cndmask_b32_e64 v41, 0, v41, s[64:65]
	v_mul_f32_e32 v1, v1, v3
	v_mul_f32_e32 v3, v51, v66
	v_fmac_f32_e32 v3, v50, v65
	v_fmac_f32_e32 v3, v52, v67
	v_fmac_f32_e32 v3, v53, v69
	v_mul_f32_e32 v5, 0xbfb8aa3b, v3
	v_exp_f32_e32 v5, v5
	v_lshlrev_b32_e32 v42, 16, v42
	v_cndmask_b32_e64 v42, 0, v42, s[66:67]
	v_lshlrev_b32_e32 v43, 16, v43
	v_add_f32_e32 v5, 1.0, v5
	v_rcp_f32_e32 v5, v5
	v_cndmask_b32_e64 v43, 0, v43, s[68:69]
	v_lshlrev_b32_e32 v44, 16, v44
	v_cndmask_b32_e64 v44, 0, v44, s[70:71]
	v_mul_f32_e32 v3, v3, v5
	v_add_u32_e32 v5, 0x400, v2
	ds_write2_b32 v5, v1, v3 offset0:4 offset1:69
	v_mul_f32_e32 v1, v52, v66
	v_fmac_f32_e32 v1, v51, v65
	v_fmac_f32_e32 v1, v53, v67
	v_fmac_f32_e32 v1, v54, v69
	v_mul_f32_e32 v3, 0xbfb8aa3b, v1
	v_exp_f32_e32 v3, v3
	v_lshlrev_b32_e32 v45, 16, v45
	v_cndmask_b32_e64 v45, 0, v45, s[72:73]
	v_lshlrev_b32_e32 v46, 16, v46
	v_add_f32_e32 v3, 1.0, v3
	v_rcp_f32_e32 v3, v3
	v_cndmask_b32_e64 v46, 0, v46, s[74:75]
	v_lshlrev_b32_e32 v47, 16, v47
	v_cndmask_b32_e64 v47, 0, v47, s[76:77]
	v_mul_f32_e32 v1, v1, v3
	v_mul_f32_e32 v3, v53, v66
	v_fmac_f32_e32 v3, v52, v65
	v_fmac_f32_e32 v3, v54, v67
	v_fmac_f32_e32 v3, v55, v69
	v_mul_f32_e32 v8, 0xbfb8aa3b, v3
	v_exp_f32_e32 v8, v8
	v_lshlrev_b32_e32 v48, 16, v48
	v_cndmask_b32_e64 v48, 0, v48, s[78:79]
	s_ashr_i32 s87, s86, 31
	v_add_f32_e32 v8, 1.0, v8
	v_rcp_f32_e32 v8, v8
	s_nop 0
	v_mul_f32_e32 v3, v3, v8
	ds_write2_b32 v5, v1, v3 offset0:134 offset1:199
	v_mul_f32_e32 v1, v54, v66
	v_fmac_f32_e32 v1, v53, v65
	v_fmac_f32_e32 v1, v55, v67
	v_fmac_f32_e32 v1, v56, v69
	v_mul_f32_e32 v3, 0xbfb8aa3b, v1
	v_exp_f32_e32 v3, v3
	s_nop 0
	v_add_f32_e32 v3, 1.0, v3
	v_rcp_f32_e32 v3, v3
	s_nop 0
	v_mul_f32_e32 v1, v1, v3
	v_mul_f32_e32 v3, v55, v66
	v_fmac_f32_e32 v3, v54, v65
	v_fmac_f32_e32 v3, v56, v67
	v_fmac_f32_e32 v3, v57, v69
	v_mul_f32_e32 v5, 0xbfb8aa3b, v3
	v_exp_f32_e32 v5, v5
	s_nop 0
	v_add_f32_e32 v5, 1.0, v5
	v_rcp_f32_e32 v5, v5
	s_nop 0
	v_mul_f32_e32 v3, v3, v5
	v_add_u32_e32 v5, 0x800, v2
	ds_write2_b32 v5, v1, v3 offset0:8 offset1:73
	v_mul_f32_e32 v1, v56, v66
	v_fmac_f32_e32 v1, v55, v65
	v_fmac_f32_e32 v1, v57, v67
	v_fmac_f32_e32 v1, v58, v69
	v_mul_f32_e32 v3, 0xbfb8aa3b, v1
	v_exp_f32_e32 v3, v3
	s_nop 0
	v_add_f32_e32 v3, 1.0, v3
	v_rcp_f32_e32 v3, v3
	s_nop 0
	v_mul_f32_e32 v1, v1, v3
	v_mul_f32_e32 v3, v57, v66
	v_fmac_f32_e32 v3, v56, v65
	v_fmac_f32_e32 v3, v58, v67
	v_fmac_f32_e32 v3, v59, v69
	v_mul_f32_e32 v8, 0xbfb8aa3b, v3
	v_exp_f32_e32 v8, v8
	s_nop 0
	v_add_f32_e32 v8, 1.0, v8
	v_rcp_f32_e32 v8, v8
	s_nop 0
	v_mul_f32_e32 v3, v3, v8
	ds_write2_b32 v5, v1, v3 offset0:138 offset1:203
	v_mul_f32_e32 v1, v58, v66
	v_fmac_f32_e32 v1, v57, v65
	v_fmac_f32_e32 v1, v59, v67
	v_fmac_f32_e32 v1, v60, v69
	v_mul_f32_e32 v3, 0xbfb8aa3b, v1
	v_exp_f32_e32 v3, v3
	s_nop 0
	v_add_f32_e32 v3, 1.0, v3
	v_rcp_f32_e32 v3, v3
	s_nop 0
	v_mul_f32_e32 v1, v1, v3
	v_mul_f32_e32 v3, v59, v66
	v_fmac_f32_e32 v3, v58, v65
	v_fmac_f32_e32 v3, v60, v67
	v_fmac_f32_e32 v3, v61, v69
	v_mul_f32_e32 v5, 0xbfb8aa3b, v3
	v_exp_f32_e32 v5, v5
	s_nop 0
	v_add_f32_e32 v5, 1.0, v5
	v_rcp_f32_e32 v5, v5
	s_nop 0
	v_mul_f32_e32 v3, v3, v5
	v_add_u32_e32 v5, 0xc00, v2
	ds_write2_b32 v5, v1, v3 offset0:12 offset1:77
	v_mul_f32_e32 v1, v60, v66
	v_fmac_f32_e32 v1, v59, v65
	v_fmac_f32_e32 v1, v61, v67
	v_fmac_f32_e32 v1, v62, v69
	v_mul_f32_e32 v3, 0xbfb8aa3b, v1
	v_exp_f32_e32 v3, v3
	s_nop 0
	v_add_f32_e32 v3, 1.0, v3
	v_rcp_f32_e32 v3, v3
	s_nop 0
	v_mul_f32_e32 v1, v1, v3
	ds_write_b32 v2, v1 offset:3640
	v_mul_f32_e32 v1, v61, v66
	v_fmac_f32_e32 v1, v60, v65
	v_fmac_f32_e32 v1, v62, v67
	v_fmac_f32_e32 v1, v63, v69
	v_mul_f32_e32 v3, 0xbfb8aa3b, v1
	v_exp_f32_e32 v3, v3
	s_nop 0
	v_add_f32_e32 v3, 1.0, v3
	v_rcp_f32_e32 v3, v3
	s_nop 0
	v_mul_f32_e32 v1, v1, v3
	v_mad_u64_u32 v[4:5], s[2:3], v4, s33, v[0:1]
	s_mov_b64 s[2:3], 0x400
	ds_write_b32 v4, v1
	v_lshl_add_u64 v[8:9], v[6:7], 0, s[2:3]
	s_movk_i32 s2, 0x1000
	s_waitcnt vmcnt(0)
	v_add_co_u32_e32 v8, vcc, s2, v6
	s_movk_i32 s2, 0x2000
	s_nop 0
	v_addc_co_u32_e32 v9, vcc, 0, v7, vcc
	v_add_co_u32_e32 v8, vcc, s2, v6
	v_mul_f32_e32 v50, v30, v205
	v_addc_co_u32_e32 v9, vcc, 0, v7, vcc
	v_fmac_f32_e32 v50, v29, v204
	s_mov_b64 vcc, 0x800
	v_fmac_f32_e32 v50, v31, v206
	v_fmac_f32_e32 v50, v32, v207
	v_mul_f32_e32 v29, 0xbfb8aa3b, v50
	v_exp_f32_e32 v29, v29
	s_nop 0
	v_add_f32_e32 v29, 1.0, v29
	v_rcp_f32_e32 v29, v29
	s_nop 0
	v_mul_f32_e32 v29, v50, v29
	v_mul_f32_e32 v50, v31, v205
	v_fmac_f32_e32 v50, v30, v204
	v_fmac_f32_e32 v50, v32, v206
	v_fmac_f32_e32 v50, v33, v207
	v_mul_f32_e32 v30, 0xbfb8aa3b, v50
	v_exp_f32_e32 v30, v30
	s_nop 0
	v_add_f32_e32 v30, 1.0, v30
	v_rcp_f32_e32 v30, v30
	s_nop 0
	v_mul_f32_e32 v30, v50, v30
	v_add_u32_e32 v50, 0x4000, v2
	ds_write2_b32 v50, v29, v30 offset0:64 offset1:129
	v_mul_f32_e32 v29, v32, v205
	v_fmac_f32_e32 v29, v31, v204
	v_fmac_f32_e32 v29, v33, v206
	v_fmac_f32_e32 v29, v35, v207
	v_mul_f32_e32 v30, 0xbfb8aa3b, v29
	v_exp_f32_e32 v30, v30
	s_nop 0
	v_add_f32_e32 v30, 1.0, v30
	v_rcp_f32_e32 v30, v30
	s_nop 0
	v_mul_f32_e32 v29, v29, v30
	v_mul_f32_e32 v30, v33, v205
	v_fmac_f32_e32 v30, v32, v204
	v_fmac_f32_e32 v30, v35, v206
	v_fmac_f32_e32 v30, v36, v207
	v_mul_f32_e32 v31, 0xbfb8aa3b, v30
	v_exp_f32_e32 v31, v31
	s_nop 0
	v_add_f32_e32 v31, 1.0, v31
	v_rcp_f32_e32 v31, v31
	s_nop 0
	v_mul_f32_e32 v30, v30, v31
	v_add_u32_e32 v31, 0x4200, v2
	ds_write2_b32 v31, v29, v30 offset0:66 offset1:131
	v_mul_f32_e32 v29, v35, v205
	v_fmac_f32_e32 v29, v33, v204
	v_fmac_f32_e32 v29, v36, v206
	v_fmac_f32_e32 v29, v37, v207
	v_mul_f32_e32 v30, 0xbfb8aa3b, v29
	v_exp_f32_e32 v30, v30
	s_nop 0
	v_add_f32_e32 v30, 1.0, v30
	v_rcp_f32_e32 v30, v30
	s_nop 0
	v_mul_f32_e32 v29, v29, v30
	v_mul_f32_e32 v30, v36, v205
	v_fmac_f32_e32 v30, v35, v204
	v_fmac_f32_e32 v30, v37, v206
	v_fmac_f32_e32 v30, v38, v207
	v_mul_f32_e32 v31, 0xbfb8aa3b, v30
	v_exp_f32_e32 v31, v31
	s_nop 0
	v_add_f32_e32 v31, 1.0, v31
	v_rcp_f32_e32 v31, v31
	s_nop 0
	v_mul_f32_e32 v30, v30, v31
	v_add_u32_e32 v31, 0x4400, v2
	ds_write2_b32 v31, v29, v30 offset0:68 offset1:133
	v_mul_f32_e32 v29, v37, v205
	v_fmac_f32_e32 v29, v36, v204
	v_fmac_f32_e32 v29, v38, v206
	v_fmac_f32_e32 v29, v39, v207
	v_mul_f32_e32 v30, 0xbfb8aa3b, v29
	v_exp_f32_e32 v30, v30
	s_nop 0
	v_add_f32_e32 v30, 1.0, v30
	v_rcp_f32_e32 v30, v30
	s_nop 0
	v_mul_f32_e32 v29, v29, v30
	v_mul_f32_e32 v30, v38, v205
	v_fmac_f32_e32 v30, v37, v204
	v_fmac_f32_e32 v30, v39, v206
	v_fmac_f32_e32 v30, v40, v207
	v_mul_f32_e32 v31, 0xbfb8aa3b, v30
	v_exp_f32_e32 v31, v31
	s_nop 0
	v_add_f32_e32 v31, 1.0, v31
	v_rcp_f32_e32 v31, v31
	s_nop 0
	v_mul_f32_e32 v30, v30, v31
	v_add_u32_e32 v31, 0x4600, v2
	ds_write2_b32 v31, v29, v30 offset0:70 offset1:135
	v_mul_f32_e32 v29, v39, v205
	v_fmac_f32_e32 v29, v38, v204
	v_fmac_f32_e32 v29, v40, v206
	v_fmac_f32_e32 v29, v41, v207
	v_mul_f32_e32 v30, 0xbfb8aa3b, v29
	v_exp_f32_e32 v30, v30
	s_nop 0
	v_add_f32_e32 v30, 1.0, v30
	v_rcp_f32_e32 v30, v30
	s_nop 0
	v_mul_f32_e32 v29, v29, v30
	v_mul_f32_e32 v30, v40, v205
	v_fmac_f32_e32 v30, v39, v204
	v_fmac_f32_e32 v30, v41, v206
	v_fmac_f32_e32 v30, v42, v207
	v_mul_f32_e32 v31, 0xbfb8aa3b, v30
	v_exp_f32_e32 v31, v31
	s_nop 0
	v_add_f32_e32 v31, 1.0, v31
	v_rcp_f32_e32 v31, v31
	s_nop 0
	v_mul_f32_e32 v30, v30, v31
	v_add_u32_e32 v31, 0x4800, v2
	ds_write2_b32 v31, v29, v30 offset0:72 offset1:137
	v_mul_f32_e32 v29, v41, v205
	v_fmac_f32_e32 v29, v40, v204
	v_fmac_f32_e32 v29, v42, v206
	v_fmac_f32_e32 v29, v43, v207
	v_mul_f32_e32 v30, 0xbfb8aa3b, v29
	v_exp_f32_e32 v30, v30
	s_nop 0
	v_add_f32_e32 v30, 1.0, v30
	v_rcp_f32_e32 v30, v30
	s_nop 0
	v_mul_f32_e32 v29, v29, v30
	v_mul_f32_e32 v30, v42, v205
	v_fmac_f32_e32 v30, v41, v204
	v_fmac_f32_e32 v30, v43, v206
	v_fmac_f32_e32 v30, v44, v207
	v_mul_f32_e32 v31, 0xbfb8aa3b, v30
	v_exp_f32_e32 v31, v31
	s_nop 0
	v_add_f32_e32 v31, 1.0, v31
	v_rcp_f32_e32 v31, v31
	s_nop 0
	v_mul_f32_e32 v30, v30, v31
	v_add_u32_e32 v31, 0x4a00, v2
	ds_write2_b32 v31, v29, v30 offset0:74 offset1:139
	v_mul_f32_e32 v29, v43, v205
	v_fmac_f32_e32 v29, v42, v204
	v_fmac_f32_e32 v29, v44, v206
	v_fmac_f32_e32 v29, v45, v207
	v_mul_f32_e32 v30, 0xbfb8aa3b, v29
	v_exp_f32_e32 v30, v30
	s_nop 0
	v_add_f32_e32 v30, 1.0, v30
	v_rcp_f32_e32 v30, v30
	s_nop 0
	v_mul_f32_e32 v29, v29, v30
	v_mul_f32_e32 v30, v44, v205
	v_fmac_f32_e32 v30, v43, v204
	v_fmac_f32_e32 v30, v45, v206
	v_fmac_f32_e32 v30, v46, v207
	v_mul_f32_e32 v31, 0xbfb8aa3b, v30
	v_exp_f32_e32 v31, v31
	s_nop 0
	v_add_f32_e32 v31, 1.0, v31
	v_rcp_f32_e32 v31, v31
	s_nop 0
	v_mul_f32_e32 v30, v30, v31
	v_add_u32_e32 v31, 0x4c00, v2
	ds_write2_b32 v31, v29, v30 offset0:76 offset1:141
	v_mul_f32_e32 v29, v45, v205
	v_mul_f32_e32 v3, v46, v205
	v_fmac_f32_e32 v29, v44, v204
	v_fmac_f32_e32 v3, v45, v204
	v_fmac_f32_e32 v29, v46, v206
	v_fmac_f32_e32 v3, v47, v206
	v_fmac_f32_e32 v29, v47, v207
	v_fmac_f32_e32 v3, v48, v207
	v_mul_f32_e32 v30, 0xbfb8aa3b, v29
	v_mul_f32_e32 v1, 0xbfb8aa3b, v3
	v_exp_f32_e32 v30, v30
	v_exp_f32_e32 v1, v1
	v_add_f32_e32 v30, 1.0, v30
	v_add_f32_e32 v1, 1.0, v1
	v_rcp_f32_e32 v30, v30
	v_rcp_f32_e32 v1, v1
	v_mul_f32_e32 v29, v29, v30
	v_mul_f32_e32 v1, v3, v1
	ds_write_b32 v2, v29 offset:20280
	ds_write_b32 v4, v1 offset:16640
	v_lshl_add_u64 v[30:31], v[6:7], 0, vcc
	s_waitcnt vmcnt(0)
	s_nop 0
	v_lshlrev_b32_e32 v8, 16, v11
	v_lshlrev_b32_e32 v7, 16, v10
	v_cndmask_b32_e64 v8, 0, v8, s[44:45]
	v_cndmask_b32_e64 v7, 0, v7, s[42:43]
	v_lshlrev_b32_e32 v9, 16, v12
	v_lshlrev_b32_e32 v11, 16, v14
	v_lshlrev_b32_e32 v14, 16, v17
	v_lshlrev_b32_e32 v17, 16, v20
	v_lshlrev_b32_e32 v20, 16, v23
	v_lshlrev_b32_e32 v23, 16, v26
	v_cndmask_b32_e64 v9, 0, v9, s[46:47]
	v_lshlrev_b32_e32 v10, 16, v13
	v_cndmask_b32_e64 v10, 0, v10, s[48:49]
	v_cndmask_b32_e64 v11, 0, v11, s[50:51]
	v_lshlrev_b32_e32 v12, 16, v15
	v_cndmask_b32_e64 v12, 0, v12, s[52:53]
	v_lshlrev_b32_e32 v13, 16, v16
	v_cndmask_b32_e64 v13, 0, v13, s[54:55]
	v_cndmask_b32_e64 v14, 0, v14, s[56:57]
	v_lshlrev_b32_e32 v15, 16, v18
	v_cndmask_b32_e64 v15, 0, v15, s[58:59]
	v_lshlrev_b32_e32 v16, 16, v19
	v_cndmask_b32_e64 v16, 0, v16, s[60:61]
	v_cndmask_b32_e64 v17, 0, v17, s[62:63]
	v_lshlrev_b32_e32 v18, 16, v21
	v_cndmask_b32_e64 v18, 0, v18, s[64:65]
	v_lshlrev_b32_e32 v19, 16, v22
	v_cndmask_b32_e64 v19, 0, v19, s[66:67]
	v_cndmask_b32_e64 v20, 0, v20, s[68:69]
	v_lshlrev_b32_e32 v21, 16, v24
	v_cndmask_b32_e64 v21, 0, v21, s[70:71]
	v_lshlrev_b32_e32 v22, 16, v25
	v_cndmask_b32_e64 v22, 0, v22, s[72:73]
	v_cndmask_b32_e64 v23, 0, v23, s[74:75]
	v_lshlrev_b32_e32 v24, 16, v27
	v_cndmask_b32_e64 v24, 0, v24, s[76:77]
	v_lshlrev_b32_e32 v25, 16, v28
	v_cndmask_b32_e64 v25, 0, v25, s[78:79]
	v_cmp_lt_i32_e64 s[42:43], 63, v68
	v_cmp_gt_i32_e64 s[44:45], 64, v68
	v_mul_f32_e32 v26, v8, v209
	v_fmac_f32_e32 v26, v7, v208
	v_fmac_f32_e32 v26, v9, v210
	v_fmac_f32_e32 v26, v10, v211
	v_mul_f32_e32 v7, 0xbfb8aa3b, v26
	v_exp_f32_e32 v7, v7
	s_nop 0
	v_add_f32_e32 v7, 1.0, v7
	v_rcp_f32_e32 v7, v7
	s_nop 0
	v_mul_f32_e32 v7, v26, v7
	v_mul_f32_e32 v26, v9, v209
	v_fmac_f32_e32 v26, v8, v208
	v_fmac_f32_e32 v26, v10, v210
	v_fmac_f32_e32 v26, v11, v211
	v_mul_f32_e32 v8, 0xbfb8aa3b, v26
	v_exp_f32_e32 v8, v8
	s_nop 0
	v_add_f32_e32 v8, 1.0, v8
	v_rcp_f32_e32 v8, v8
	s_nop 0
	v_mul_f32_e32 v8, v26, v8
	v_add_u32_e32 v26, 0x8000, v2
	ds_write2_b32 v26, v7, v8 offset0:128 offset1:193
	v_mul_f32_e32 v7, v10, v209
	v_fmac_f32_e32 v7, v9, v208
	v_fmac_f32_e32 v7, v11, v210
	v_fmac_f32_e32 v7, v12, v211
	v_mul_f32_e32 v8, 0xbfb8aa3b, v7
	v_exp_f32_e32 v8, v8
	s_nop 0
	v_add_f32_e32 v8, 1.0, v8
	v_rcp_f32_e32 v8, v8
	s_nop 0
	v_mul_f32_e32 v7, v7, v8
	v_mul_f32_e32 v8, v11, v209
	v_fmac_f32_e32 v8, v10, v208
	v_fmac_f32_e32 v8, v12, v210
	v_fmac_f32_e32 v8, v13, v211
	v_mul_f32_e32 v9, 0xbfb8aa3b, v8
	v_exp_f32_e32 v9, v9
	s_nop 0
	v_add_f32_e32 v9, 1.0, v9
	v_rcp_f32_e32 v9, v9
	s_nop 0
	v_mul_f32_e32 v8, v8, v9
	v_add_u32_e32 v9, 0x8400, v2
	ds_write2_b32 v9, v7, v8 offset0:2 offset1:67
	v_mul_f32_e32 v7, v12, v209
	v_fmac_f32_e32 v7, v11, v208
	v_fmac_f32_e32 v7, v13, v210
	v_fmac_f32_e32 v7, v14, v211
	v_mul_f32_e32 v8, 0xbfb8aa3b, v7
	v_exp_f32_e32 v8, v8
	s_nop 0
	v_add_f32_e32 v8, 1.0, v8
	v_rcp_f32_e32 v8, v8
	s_nop 0
	v_mul_f32_e32 v7, v7, v8
	v_mul_f32_e32 v8, v13, v209
	v_fmac_f32_e32 v8, v12, v208
	v_fmac_f32_e32 v8, v14, v210
	v_fmac_f32_e32 v8, v15, v211
	v_mul_f32_e32 v10, 0xbfb8aa3b, v8
	v_exp_f32_e32 v10, v10
	s_nop 0
	v_add_f32_e32 v10, 1.0, v10
	v_rcp_f32_e32 v10, v10
	s_nop 0
	v_mul_f32_e32 v8, v8, v10
	ds_write2_b32 v9, v7, v8 offset0:132 offset1:197
	v_mul_f32_e32 v7, v14, v209
	v_fmac_f32_e32 v7, v13, v208
	v_fmac_f32_e32 v7, v15, v210
	v_fmac_f32_e32 v7, v16, v211
	v_mul_f32_e32 v8, 0xbfb8aa3b, v7
	v_exp_f32_e32 v8, v8
	s_nop 0
	v_add_f32_e32 v8, 1.0, v8
	v_rcp_f32_e32 v8, v8
	s_nop 0
	v_mul_f32_e32 v7, v7, v8
	v_mul_f32_e32 v8, v15, v209
	v_fmac_f32_e32 v8, v14, v208
	v_fmac_f32_e32 v8, v16, v210
	v_fmac_f32_e32 v8, v17, v211
	v_mul_f32_e32 v9, 0xbfb8aa3b, v8
	v_exp_f32_e32 v9, v9
	s_nop 0
	v_add_f32_e32 v9, 1.0, v9
	v_rcp_f32_e32 v9, v9
	s_nop 0
	v_mul_f32_e32 v8, v8, v9
	v_add_u32_e32 v9, 0x8800, v2
	ds_write2_b32 v9, v7, v8 offset0:6 offset1:71
	v_mul_f32_e32 v7, v16, v209
	v_fmac_f32_e32 v7, v15, v208
	v_fmac_f32_e32 v7, v17, v210
	v_fmac_f32_e32 v7, v18, v211
	v_mul_f32_e32 v8, 0xbfb8aa3b, v7
	v_exp_f32_e32 v8, v8
	s_nop 0
	v_add_f32_e32 v8, 1.0, v8
	v_rcp_f32_e32 v8, v8
	s_nop 0
	v_mul_f32_e32 v7, v7, v8
	v_mul_f32_e32 v8, v17, v209
	v_fmac_f32_e32 v8, v16, v208
	v_fmac_f32_e32 v8, v18, v210
	v_fmac_f32_e32 v8, v19, v211
	v_mul_f32_e32 v10, 0xbfb8aa3b, v8
	v_exp_f32_e32 v10, v10
	s_nop 0
	v_add_f32_e32 v10, 1.0, v10
	v_rcp_f32_e32 v10, v10
	s_nop 0
	v_mul_f32_e32 v8, v8, v10
	ds_write2_b32 v9, v7, v8 offset0:136 offset1:201
	v_mul_f32_e32 v7, v18, v209
	v_fmac_f32_e32 v7, v17, v208
	v_fmac_f32_e32 v7, v19, v210
	v_fmac_f32_e32 v7, v20, v211
	v_mul_f32_e32 v8, 0xbfb8aa3b, v7
	v_exp_f32_e32 v8, v8
	s_nop 0
	v_add_f32_e32 v8, 1.0, v8
	v_rcp_f32_e32 v8, v8
	s_nop 0
	v_mul_f32_e32 v7, v7, v8
	v_mul_f32_e32 v8, v19, v209
	v_fmac_f32_e32 v8, v18, v208
	v_fmac_f32_e32 v8, v20, v210
	v_fmac_f32_e32 v8, v21, v211
	v_mul_f32_e32 v9, 0xbfb8aa3b, v8
	v_exp_f32_e32 v9, v9
	s_nop 0
	v_add_f32_e32 v9, 1.0, v9
	v_rcp_f32_e32 v9, v9
	s_nop 0
	v_mul_f32_e32 v8, v8, v9
	v_add_u32_e32 v9, 0x8c00, v2
	ds_write2_b32 v9, v7, v8 offset0:10 offset1:75
	v_mul_f32_e32 v7, v20, v209
	v_fmac_f32_e32 v7, v19, v208
	v_fmac_f32_e32 v7, v21, v210
	v_fmac_f32_e32 v7, v22, v211
	v_mul_f32_e32 v8, 0xbfb8aa3b, v7
	v_exp_f32_e32 v8, v8
	s_nop 0
	v_add_f32_e32 v8, 1.0, v8
	v_rcp_f32_e32 v8, v8
	s_nop 0
	v_mul_f32_e32 v7, v7, v8
	v_mul_f32_e32 v8, v21, v209
	v_fmac_f32_e32 v8, v20, v208
	v_fmac_f32_e32 v8, v22, v210
	v_fmac_f32_e32 v8, v23, v211
	v_mul_f32_e32 v10, 0xbfb8aa3b, v8
	v_exp_f32_e32 v10, v10
	s_nop 0
	v_add_f32_e32 v10, 1.0, v10
	v_rcp_f32_e32 v10, v10
	s_nop 0
	v_mul_f32_e32 v8, v8, v10
	ds_write2_b32 v9, v7, v8 offset0:140 offset1:205
	v_mul_f32_e32 v7, v22, v209
	v_fmac_f32_e32 v7, v21, v208
	v_fmac_f32_e32 v7, v23, v210
	v_fmac_f32_e32 v7, v24, v211
	v_mul_f32_e32 v8, 0xbfb8aa3b, v7
	v_exp_f32_e32 v8, v8
	s_nop 0
	v_add_f32_e32 v8, 1.0, v8
	v_rcp_f32_e32 v8, v8
	s_nop 0
	v_mul_f32_e32 v7, v7, v8
	ds_write_b32 v2, v7 offset:36920
	v_mul_f32_e32 v2, v23, v209
	v_fmac_f32_e32 v2, v22, v208
	v_fmac_f32_e32 v2, v24, v210
	v_fmac_f32_e32 v2, v25, v211
	v_mul_f32_e32 v1, 0xbfb8aa3b, v2
	v_exp_f32_e32 v1, v1
	s_nop 0
	v_add_f32_e32 v1, 1.0, v1
	v_rcp_f32_e32 v1, v1
	s_nop 0
	v_mul_f32_e32 v1, v2, v1
	ds_write_b32 v4, v1 offset:33280
	v_lshlrev_b32_e32 v1, 2, v68
	v_mov_b32_e32 v3, v210
	v_mov_b32_e32 v5, v209
	v_mov_b32_e32 v6, v211
	v_mov_b32_e32 v49, v207
	s_and_saveexec_b64 s[46:47], s[44:45]
	s_cbranch_execz .LBB0_368
	v_ashrrev_i32_e32 v69, 31, v68
	v_lshl_add_u64 v[2:3], s[40:41], 0, v[68:69]
	s_load_dwordx4 s[48:51], s[36:37], 0x28
	v_lshlrev_b64 v[2:3], 7, v[2:3]
	v_lshl_add_u64 v[2:3], s[80:81], 0, v[2:3]
	s_lshl_b32 s84, s26, 2
	v_lshl_add_u64 v[2:3], v[2:3], 0, s[84:85]
	s_or_b32 s84, s26, s94
	s_mov_b64 s[2:3], 0x10000000
	s_lshl_b64 s[40:41], s[84:85], 2
	v_lshl_add_u64 v[4:5], v[2:3], 0, s[2:3]
	s_waitcnt lgkmcnt(0)
	s_add_u32 s2, s50, s40
	v_add_co_u32_e32 v2, vcc, 0x10000000, v2
	s_addc_u32 s3, s51, s41
	s_nop 0
	v_addc_co_u32_e32 v3, vcc, 0, v3, vcc
	global_load_dword v4, v[4:5], off offset:16
	v_add_u32_e32 v10, -1, v229
	global_load_dword v2, v[2:3], off
	v_and_b32_e32 v3, 64, v229
	global_load_dword v5, v129, s[2:3]
	s_add_u32 s2, s48, s40
	s_addc_u32 s3, s49, s41
	global_load_dword v6, v129, s[2:3]
	s_mov_b32 s2, 0xbfb8aa3b
	s_mov_b32 s3, 0x3f2aaaab
	v_cmp_lt_i32_e32 vcc, v10, v3
	s_mov_b32 s26, 0x3f317218
	v_mov_b32_e32 v7, 0x3ecc95a3
	v_cndmask_b32_e32 v10, v10, v229, vcc
	s_mov_b32 s27, 0x7f800000
	v_mov_b32_e32 v8, 0x7fc00000
	v_mov_b32_e32 v9, 0xff800000
	s_mov_b32 s28, 0x33800000
	v_lshlrev_b32_e32 v10, 2, v10
	s_waitcnt vmcnt(2)
	v_mul_f32_e32 v2, 0xbfb8aa3b, v2
	v_exp_f32_e32 v2, v2
	s_waitcnt vmcnt(1)
	v_add_f32_e32 v4, v4, v5
	v_mul_f32_e64 v5, |v4|, s2
	v_exp_f32_e32 v11, v5
	v_max_f32_e32 v12, 0, v4
	s_waitcnt vmcnt(0)
	v_mul_f32_e32 v4, 0x3fb8aa3b, v6
	v_exp_f32_e32 v6, v4
	v_add_f32_e32 v13, 1.0, v11
	v_add_f32_e32 v14, -1.0, v13
	v_frexp_mant_f32_e32 v15, v13
	v_cvt_f64_f32_e32 v[4:5], v13
	v_sub_f32_e32 v16, v14, v13
	v_frexp_exp_i32_f64_e32 v4, v[4:5]
	v_cmp_gt_f32_e32 vcc, s3, v15
	v_sub_f32_e32 v14, v11, v14
	v_add_f32_e32 v5, 1.0, v16
	v_subbrev_co_u32_e32 v4, vcc, 0, v4, vcc
	v_add_f32_e32 v5, v14, v5
	v_sub_u32_e32 v14, 0, v4
	v_cvt_f32_i32_e32 v4, v4
	v_ldexp_f32 v13, v13, v14
	v_ldexp_f32 v5, v5, v14
	v_add_f32_e32 v14, -1.0, v13
	v_add_f32_e32 v15, 1.0, v13
	v_add_f32_e32 v16, 1.0, v14
	v_add_f32_e32 v17, -1.0, v15
	v_sub_f32_e32 v16, v13, v16
	v_sub_f32_e32 v13, v13, v17
	v_mul_f32_e32 v17, 0x3f317218, v4
	v_add_f32_e32 v16, v5, v16
	v_add_f32_e32 v5, v5, v13
	v_fma_f32 v13, v4, s26, -v17
	v_add_f32_e32 v18, v14, v16
	v_add_f32_e32 v19, v15, v5
	v_fmac_f32_e32 v13, 0xb102e308, v4
	v_sub_f32_e32 v4, v18, v14
	v_sub_f32_e32 v14, v19, v15
	v_rcp_f32_e32 v15, v19
	v_add_f32_e32 v20, v17, v13
	v_sub_f32_e32 v5, v5, v14
	v_sub_f32_e32 v14, v20, v17
	v_sub_f32_e32 v13, v13, v14
	v_mul_f32_e32 v14, v18, v15
	v_sub_f32_e32 v4, v16, v4
	v_mul_f32_e32 v16, v19, v14
	v_fma_f32 v17, v14, v19, -v16
	v_fmac_f32_e32 v17, v14, v5
	v_add_f32_e32 v21, v16, v17
	v_sub_f32_e32 v22, v18, v21
	v_sub_f32_e32 v16, v21, v16
	v_sub_f32_e32 v18, v18, v22
	v_sub_f32_e32 v16, v16, v17
	v_sub_f32_e32 v17, v18, v21
	v_add_f32_e32 v4, v4, v17
	v_add_f32_e32 v4, v16, v4
	v_add_f32_e32 v16, v22, v4
	v_mul_f32_e32 v17, v15, v16
	v_sub_f32_e32 v18, v22, v16
	v_mul_f32_e32 v21, v19, v17
	v_add_f32_e32 v4, v4, v18
	v_add_f32_e32 v18, v14, v17
	v_fma_f32 v19, v17, v19, -v21
	v_sub_f32_e32 v14, v18, v14
	v_fmac_f32_e32 v19, v17, v5
	v_sub_f32_e32 v5, v17, v14
	v_add_f32_e32 v14, v21, v19
	v_sub_f32_e32 v17, v14, v21
	v_sub_f32_e32 v21, v16, v14
	v_sub_f32_e32 v16, v16, v21
	v_sub_f32_e32 v14, v16, v14
	v_sub_f32_e32 v17, v17, v19
	v_add_f32_e32 v4, v4, v14
	v_add_f32_e32 v4, v17, v4
	v_add_f32_e32 v4, v21, v4
	v_mul_f32_e32 v4, v15, v4
	v_add_f32_e32 v4, v5, v4
	v_add_f32_e32 v5, v18, v4
	v_mul_f32_e32 v14, v5, v5
	v_fmamk_f32 v7, v14, 0x3e9b6dac, v7
	v_sub_f32_e32 v15, v5, v18
	v_ldexp_f32 v16, v5, 1
	v_mul_f32_e32 v5, v5, v14
	v_fmaak_f32 v7, v14, v7, 0x3f2aaada
	v_mul_f32_e32 v5, v5, v7
	v_add_f32_e32 v7, v16, v5
	v_sub_f32_e32 v4, v4, v15
	v_sub_f32_e32 v14, v7, v16
	v_ldexp_f32 v4, v4, 1
	v_sub_f32_e32 v5, v5, v14
	v_add_f32_e32 v4, v4, v5
	v_add_f32_e32 v5, v7, v4
	v_sub_f32_e32 v7, v5, v7
	v_add_f32_e32 v14, v20, v5
	v_sub_f32_e32 v4, v4, v7
	v_sub_f32_e32 v7, v14, v20
	v_sub_f32_e32 v15, v14, v7
	v_sub_f32_e32 v5, v5, v7
	v_add_f32_e32 v7, v13, v4
	v_sub_f32_e32 v15, v20, v15
	v_sub_f32_e32 v16, v7, v13
	v_add_f32_e32 v5, v5, v15
	v_sub_f32_e32 v15, v7, v16
	v_add_f32_e32 v5, v7, v5
	v_sub_f32_e32 v4, v4, v16
	v_sub_f32_e32 v13, v13, v15
	v_add_f32_e32 v7, v14, v5
	v_add_f32_e32 v4, v4, v13
	v_sub_f32_e32 v13, v7, v14
	v_sub_f32_e32 v5, v5, v13
	v_add_f32_e32 v4, v4, v5
	v_add_f32_e32 v4, v7, v4
	v_cmp_neq_f32_e32 vcc, s27, v11
	v_add_f32_e32 v2, 1.0, v2
	s_nop 0
	v_cndmask_b32_e32 v4, v228, v4, vcc
	v_cmp_ngt_f32_e32 vcc, -1.0, v11
	s_nop 1
	v_cndmask_b32_e32 v4, v8, v4, vcc
	v_cmp_neq_f32_e32 vcc, -1.0, v11
	v_add_u32_e32 v8, -2, v229
	s_nop 0
	v_cndmask_b32_e32 v4, v9, v4, vcc
	v_cmp_lt_f32_e64 vcc, |v11|, s28
	s_nop 1
	v_cndmask_b32_e32 v4, v4, v11, vcc
	v_add_f32_e32 v4, v12, v4
	v_mul_f32_e64 v5, v4, -v6
	ds_bpermute_b32 v7, v10, v5
	v_cmp_lt_i32_e32 vcc, v8, v3
	s_waitcnt lgkmcnt(0)
	v_fma_f32 v4, v4, -v6, v7
	v_cndmask_b32_e32 v8, v8, v229, vcc
	v_cmp_eq_u32_e32 vcc, 0, v34
	v_lshlrev_b32_e32 v8, 2, v8
	v_add_u32_e32 v6, -4, v229
	v_cndmask_b32_e32 v4, v4, v5, vcc
	ds_bpermute_b32 v5, v8, v4
	v_cmp_lt_i32_e32 vcc, v6, v3
	s_waitcnt lgkmcnt(0)
	v_add_f32_e32 v5, v4, v5
	v_cndmask_b32_e32 v6, v6, v229, vcc
	v_cmp_gt_u32_e32 vcc, 2, v34
	s_nop 1
	v_cndmask_b32_e32 v4, v5, v4, vcc
	v_lshlrev_b32_e32 v5, 2, v6
	ds_bpermute_b32 v5, v5, v4
	v_add_u32_e32 v6, -8, v229
	v_cmp_gt_u32_e32 vcc, 4, v34
	s_waitcnt lgkmcnt(0)
	v_add_f32_e32 v5, v4, v5
	v_cndmask_b32_e32 v4, v5, v4, vcc
	v_cmp_lt_i32_e32 vcc, v6, v3
	s_nop 1
	v_cndmask_b32_e32 v5, v6, v229, vcc
	v_lshlrev_b32_e32 v5, 2, v5
	ds_bpermute_b32 v5, v5, v4
	v_add_u32_e32 v6, -16, v229
	v_cmp_gt_u32_e32 vcc, 8, v34
	s_waitcnt lgkmcnt(0)
	v_add_f32_e32 v5, v4, v5
	v_cndmask_b32_e32 v4, v5, v4, vcc
	v_cmp_lt_i32_e32 vcc, v6, v3
	s_nop 1
	v_cndmask_b32_e32 v5, v6, v229, vcc
	v_lshlrev_b32_e32 v5, 2, v5
	ds_bpermute_b32 v5, v5, v4
	v_cmp_gt_u32_e32 vcc, 16, v34
	s_waitcnt lgkmcnt(0)
	v_add_f32_e32 v5, v4, v5
	v_cndmask_b32_e32 v4, v5, v4, vcc
	v_subrev_u32_e32 v5, 32, v229
	v_cmp_lt_i32_e32 vcc, v5, v3
	s_nop 1
	v_cndmask_b32_e32 v3, v5, v229, vcc
	v_lshlrev_b32_e32 v3, 2, v3
	ds_bpermute_b32 v3, v3, v4
	v_cmp_gt_u32_e32 vcc, 32, v34
	v_add_u32_e32 v5, 0x10300, v1
	s_waitcnt lgkmcnt(0)
	v_add_f32_e32 v3, v4, v3
	v_cndmask_b32_e32 v3, v3, v4, vcc
	v_rcp_f32_e32 v4, v2
	v_mul_f32_e32 v2, 0x3fb8aa3b, v3
	v_exp_f32_e32 v2, v2
	ds_write_b32 v5, v3
	v_add_u32_e32 v3, 0x10400, v1
	ds_write_b32 v3, v4
	v_add_u32_e32 v3, 0x10500, v1
	ds_write_b32 v3, v2
	v_mul_f32_e32 v3, v4, v2
	v_add_u32_e32 v4, 0x10600, v1
	v_cmp_eq_u32_e32 vcc, 63, v68
	ds_write_b32 v4, v3
	s_and_b64 exec, exec, vcc
	s_cbranch_execz .LBB0_368
	s_lshl_b64 s[2:3], s[86:87], 2
	s_add_u32 s2, s80, s2
	s_addc_u32 s3, s81, s3
	global_store_dword v225, v2, s[2:3]
